# hand-written candidate rank-count block (VOP3 cmp/addc pipelined, T-limited, zero-padded tail)
# speedup vs baseline: 1.0685x; 1.0124x over previous
; #define LAS __attribute__((address_space(3)))
; __device__ __forceinline__ void dsa_unit(const Params& p, LAS unsigned char* lds, int b, int c) {
;     ...
;             for (int i = 0; i < 8; ++i) { const int q2 = 8 * wid + i; const int n = (int)ceqv[q2], r = (int)remv[q2];
;                 LAS const unsigned* cd = (LAS const unsigned*)(lds + DS_CAND) + q2 * DS_CAP;
;                 unsigned kk[4]; int rank[4];
; #pragma unroll
;                 for (int t = 0; t < 4; ++t) { kk[t] = (lane + 64 * t < n) ? cd[lane + 64 * t] : 0xFFFFFFFFu; rank[t] = 0; }
;                 for (int j = 0; j < n; j += 4) { u32x4 v = *(LAS const u32x4*)(cd + j);
; #pragma unroll
;                     for (int e = 0; e < 4; ++e) { const unsigned ve = (j + e < n) ? v[e] : 0u;
; #pragma unroll
;                         for (int t = 0; t < 4; ++t) rank[t] += (ve > kk[t]) ? 1 : 0; } }
; #pragma unroll
;                 for (int t = 0; t < 4; ++t) if (lane + 64 * t < n && rank[t] < r) selall[q2 * 256 + (256 - r) + rank[t]] = (unsigned short)(8191u - (kk[t] & 0x1FFFu)); }
.LBB0_1621:
	s_and_b64 vcc, exec, s[0:1]
	s_waitcnt lgkmcnt(0)
	s_barrier
	s_cbranch_vccnz .LBB0_1815
	v_mbcnt_lo_u32_b32 v0, -1, 0
	v_mbcnt_hi_u32_b32 v0, -1, v0
	s_mov_b32 s18, 0
.Lrk_q:
	s_add_i32 s0, s30, s18
	s_lshl_b32 s1, s0, 2
	s_add_i32 s2, s1, 0x18500
	s_add_i32 s3, s1, 0x18300
	v_mov_b32_e32 v9, s2
	v_mov_b32_e32 v10, s3
	ds_read_b32 v9, v9
	ds_read_b32 v10, v10
	s_lshl_b32 s23, s0, 10
	s_addk_i32 s23, 0x100
	s_lshl_b32 s24, s0, 9
	s_add_i32 s24, s24, 0x10200
	s_waitcnt lgkmcnt(0)
	v_readfirstlane_b32 s19, v9
	v_readfirstlane_b32 s20, v10
	v_lshl_add_u32 v11, v0, 2, s23
	s_cmp_lt_i32 s19, 1
	s_cbranch_scc1 .Lrk_next
	v_add_u32_e32 v9, s19, v0
	v_cmp_gt_u32_e32 vcc, 8, v0
	s_mov_b64 s[0:1], vcc
	v_cmp_gt_u32_e32 vcc, 0x100, v9
	s_and_b64 s[0:1], s[0:1], vcc
	v_mov_b32_e32 v10, 0
	v_lshl_add_u32 v9, v9, 2, s23
	s_mov_b64 exec, s[0:1]
	ds_write_b32 v9, v10
	s_mov_b64 exec, -1
	v_mov_b32_e32 v1, -1
	v_mov_b32_e32 v2, -1
	v_mov_b32_e32 v3, -1
	v_mov_b32_e32 v4, -1
	v_cmp_gt_i32_e32 vcc, s19, v0
	s_mov_b64 exec, vcc
	ds_read_b32 v1, v11
	s_mov_b64 exec, -1
	v_add_u32_e32 v9, 64, v0
	v_cmp_gt_i32_e32 vcc, s19, v9
	s_mov_b64 exec, vcc
	ds_read_b32 v2, v11 offset:256
	s_mov_b64 exec, -1
	v_add_u32_e32 v9, 128, v0
	v_cmp_gt_i32_e32 vcc, s19, v9
	s_mov_b64 exec, vcc
	ds_read_b32 v3, v11 offset:512
	s_mov_b64 exec, -1
	v_add_u32_e32 v9, 192, v0
	v_cmp_gt_i32_e32 vcc, s19, v9
	s_mov_b64 exec, vcc
	ds_read_b32 v4, v11 offset:768
	s_mov_b64 exec, -1
	v_mov_b32_e32 v5, 0
	v_mov_b32_e32 v6, 0
	v_mov_b32_e32 v7, 0
	v_mov_b32_e32 v8, 0
	s_add_i32 s22, s19, 63
	s_lshr_b32 s22, s22, 6
	s_add_i32 s21, s19, 7
	s_lshr_b32 s21, s21, 3
	v_mov_b32_e32 v9, s23
	ds_read_b128 v[12:15], v9
.Lrk_j:
	ds_read_b128 v[16:19], v9 offset:16
	v_add_u32_e32 v9, 32, v9
	s_waitcnt lgkmcnt(1)
	v_cmp_gt_u32_e64 s[0:1], v12, v1
	v_cmp_gt_u32_e64 s[2:3], v13, v1
	v_cmp_gt_u32_e64 s[40:41], v14, v1
	v_cmp_gt_u32_e64 s[42:43], v15, v1
	v_addc_co_u32_e64 v5, s[0:1], 0, v5, s[0:1]
	v_addc_co_u32_e64 v5, s[2:3], 0, v5, s[2:3]
	v_addc_co_u32_e64 v5, s[40:41], 0, v5, s[40:41]
	v_addc_co_u32_e64 v5, s[42:43], 0, v5, s[42:43]
	s_cmp_lt_u32 s22, 2
	s_cbranch_scc1 .Lrk_a_end
	v_cmp_gt_u32_e64 s[0:1], v12, v2
	v_cmp_gt_u32_e64 s[2:3], v13, v2
	v_cmp_gt_u32_e64 s[40:41], v14, v2
	v_cmp_gt_u32_e64 s[42:43], v15, v2
	v_addc_co_u32_e64 v6, s[0:1], 0, v6, s[0:1]
	v_addc_co_u32_e64 v6, s[2:3], 0, v6, s[2:3]
	v_addc_co_u32_e64 v6, s[40:41], 0, v6, s[40:41]
	v_addc_co_u32_e64 v6, s[42:43], 0, v6, s[42:43]
	s_cmp_lt_u32 s22, 3
	s_cbranch_scc1 .Lrk_a_end
	v_cmp_gt_u32_e64 s[0:1], v12, v3
	v_cmp_gt_u32_e64 s[2:3], v13, v3
	v_cmp_gt_u32_e64 s[40:41], v14, v3
	v_cmp_gt_u32_e64 s[42:43], v15, v3
	v_addc_co_u32_e64 v7, s[0:1], 0, v7, s[0:1]
	v_addc_co_u32_e64 v7, s[2:3], 0, v7, s[2:3]
	v_addc_co_u32_e64 v7, s[40:41], 0, v7, s[40:41]
	v_addc_co_u32_e64 v7, s[42:43], 0, v7, s[42:43]
	s_cmp_lt_u32 s22, 4
	s_cbranch_scc1 .Lrk_a_end
	v_cmp_gt_u32_e64 s[0:1], v12, v4
	v_cmp_gt_u32_e64 s[2:3], v13, v4
	v_cmp_gt_u32_e64 s[40:41], v14, v4
	v_cmp_gt_u32_e64 s[42:43], v15, v4
	v_addc_co_u32_e64 v8, s[0:1], 0, v8, s[0:1]
	v_addc_co_u32_e64 v8, s[2:3], 0, v8, s[2:3]
	v_addc_co_u32_e64 v8, s[40:41], 0, v8, s[40:41]
	v_addc_co_u32_e64 v8, s[42:43], 0, v8, s[42:43]
.Lrk_a_end:
	ds_read_b128 v[12:15], v9
	s_waitcnt lgkmcnt(1)
	v_cmp_gt_u32_e64 s[0:1], v16, v1
	v_cmp_gt_u32_e64 s[2:3], v17, v1
	v_cmp_gt_u32_e64 s[40:41], v18, v1
	v_cmp_gt_u32_e64 s[42:43], v19, v1
	v_addc_co_u32_e64 v5, s[0:1], 0, v5, s[0:1]
	v_addc_co_u32_e64 v5, s[2:3], 0, v5, s[2:3]
	v_addc_co_u32_e64 v5, s[40:41], 0, v5, s[40:41]
	v_addc_co_u32_e64 v5, s[42:43], 0, v5, s[42:43]
	s_cmp_lt_u32 s22, 2
	s_cbranch_scc1 .Lrk_b_end
	v_cmp_gt_u32_e64 s[0:1], v16, v2
	v_cmp_gt_u32_e64 s[2:3], v17, v2
	v_cmp_gt_u32_e64 s[40:41], v18, v2
	v_cmp_gt_u32_e64 s[42:43], v19, v2
	v_addc_co_u32_e64 v6, s[0:1], 0, v6, s[0:1]
	v_addc_co_u32_e64 v6, s[2:3], 0, v6, s[2:3]
	v_addc_co_u32_e64 v6, s[40:41], 0, v6, s[40:41]
	v_addc_co_u32_e64 v6, s[42:43], 0, v6, s[42:43]
	s_cmp_lt_u32 s22, 3
	s_cbranch_scc1 .Lrk_b_end
	v_cmp_gt_u32_e64 s[0:1], v16, v3
	v_cmp_gt_u32_e64 s[2:3], v17, v3
	v_cmp_gt_u32_e64 s[40:41], v18, v3
	v_cmp_gt_u32_e64 s[42:43], v19, v3
	v_addc_co_u32_e64 v7, s[0:1], 0, v7, s[0:1]
	v_addc_co_u32_e64 v7, s[2:3], 0, v7, s[2:3]
	v_addc_co_u32_e64 v7, s[40:41], 0, v7, s[40:41]
	v_addc_co_u32_e64 v7, s[42:43], 0, v7, s[42:43]
	s_cmp_lt_u32 s22, 4
	s_cbranch_scc1 .Lrk_b_end
	v_cmp_gt_u32_e64 s[0:1], v16, v4
	v_cmp_gt_u32_e64 s[2:3], v17, v4
	v_cmp_gt_u32_e64 s[40:41], v18, v4
	v_cmp_gt_u32_e64 s[42:43], v19, v4
	v_addc_co_u32_e64 v8, s[0:1], 0, v8, s[0:1]
	v_addc_co_u32_e64 v8, s[2:3], 0, v8, s[2:3]
	v_addc_co_u32_e64 v8, s[40:41], 0, v8, s[40:41]
	v_addc_co_u32_e64 v8, s[42:43], 0, v8, s[42:43]
.Lrk_b_end:
	s_add_i32 s21, s21, -1
	s_cmp_lg_u32 s21, 0
	s_cbranch_scc1 .Lrk_j
	s_waitcnt lgkmcnt(0)
	s_lshl_b32 s2, s20, 1
	s_sub_i32 s2, s24, s2
	s_addk_i32 s2, 0x200
	v_mov_b32_e32 v12, 0x1fff
	v_cmp_gt_i32_e32 vcc, s19, v0
	v_cmp_gt_u32_e64 s[0:1], s20, v5
	v_bitop3_b32 v11, v1, v12, v12 bitop3:0xc
	v_lshl_add_u32 v10, v5, 1, s2
	s_and_b64 s[0:1], s[0:1], vcc
	s_mov_b64 exec, s[0:1]
	ds_write_b16 v10, v11
	s_mov_b64 exec, -1
	s_cmp_lt_u32 s22, 2
	s_cbranch_scc1 .Lrk_next
	v_add_u32_e32 v9, 64, v0
	v_cmp_gt_i32_e32 vcc, s19, v9
	v_cmp_gt_u32_e64 s[0:1], s20, v6
	v_bitop3_b32 v11, v2, v12, v12 bitop3:0xc
	v_lshl_add_u32 v10, v6, 1, s2
	s_and_b64 s[0:1], s[0:1], vcc
	s_mov_b64 exec, s[0:1]
	ds_write_b16 v10, v11
	s_mov_b64 exec, -1
	s_cmp_lt_u32 s22, 3
	s_cbranch_scc1 .Lrk_next
	v_add_u32_e32 v9, 128, v0
	v_cmp_gt_i32_e32 vcc, s19, v9
	v_cmp_gt_u32_e64 s[0:1], s20, v7
	v_bitop3_b32 v11, v3, v12, v12 bitop3:0xc
	v_lshl_add_u32 v10, v7, 1, s2
	s_and_b64 s[0:1], s[0:1], vcc
	s_mov_b64 exec, s[0:1]
	ds_write_b16 v10, v11
	s_mov_b64 exec, -1
	s_cmp_lt_u32 s22, 4
	s_cbranch_scc1 .Lrk_next
	v_add_u32_e32 v9, 192, v0
	v_cmp_gt_i32_e32 vcc, s19, v9
	v_cmp_gt_u32_e64 s[0:1], s20, v8
	v_bitop3_b32 v11, v4, v12, v12 bitop3:0xc
	v_lshl_add_u32 v10, v8, 1, s2
	s_and_b64 s[0:1], s[0:1], vcc
	s_mov_b64 exec, s[0:1]
	ds_write_b16 v10, v11
	s_mov_b64 exec, -1
.Lrk_next:
	s_add_i32 s18, s18, 1
	s_cmp_lt_u32 s18, 8
	s_cbranch_scc1 .Lrk_q
	s_waitcnt lgkmcnt(0)
